# cache-policy A/B: P0 RMSNorm x-row loads with nt
# baseline (speedup 1.0000x reference)
.LBB0_30:
	global_load_dwordx4 v[24:27], v32, s[12:13] nt
	global_load_dwordx4 v[4:7], v32, s[12:13] offset:1024 nt
	global_load_dwordx4 v[20:23], v32, s[12:13] offset:2048 nt
	global_load_dwordx4 v[8:11], v32, s[12:13] offset:3072 nt
	v_lshl_add_u64 v[0:1], s[12:13], 0, v[32:33]
	v_add_co_u32_e32 v16, vcc, s15, v0
	s_lshl_b64 s[12:13], s[4:5], 12
	s_nop 0
	v_addc_co_u32_e32 v17, vcc, 0, v1, vcc
	global_load_dwordx4 v[12:15], v[16:17], off offset:1024 nt
	global_load_dwordx4 v[28:31], v[16:17], off nt
	global_load_dwordx4 v[0:3], v[16:17], off offset:3072 nt
	s_nop 0
	global_load_dwordx4 v[16:19], v[16:17], off offset:2048 nt
	s_nop 0
	global_load_dwordx4 v[56:59], v[34:35], off nt
	s_add_u32 s0, s0, s70
	s_addc_u32 s1, s1, s71
	s_add_u32 s8, s8, s10
	s_addc_u32 s9, s9, s11
	s_cmpk_gt_i32 s0, 0x201f
	s_waitcnt vmcnt(8)
	v_mov_b32_e32 v62, v25
	s_waitcnt vmcnt(7)
	v_mov_b32_e32 v63, v5
	v_mov_b32_e32 v66, v27
	v_mov_b32_e32 v67, v7
	v_mov_b32_e32 v60, v24
	v_mov_b32_e32 v61, v4
	v_mov_b32_e32 v64, v26
	v_mov_b32_e32 v65, v6
	s_waitcnt vmcnt(6)
	v_pk_mul_f32 v[68:69], v[22:23], v[22:23]
	v_pk_mul_f32 v[70:71], v[20:21], v[20:21]
	v_pk_mul_f32 v[62:63], v[62:63], v[62:63]
	v_pk_mul_f32 v[66:67], v[66:67], v[66:67]
	v_pk_mov_b32 v[76:77], v[70:71], v[68:69] op_sel:[1,0]
	v_mov_b32_e32 v71, v69
	v_pk_fma_f32 v[60:61], v[60:61], v[60:61], v[62:63]
	v_pk_fma_f32 v[62:63], v[64:65], v[64:65], v[66:67]
	s_waitcnt vmcnt(5)
	v_mul_f32_e32 v72, v9, v9
	v_mul_f32_e32 v74, v11, v11
	v_pk_add_f32 v[64:65], v[76:77], v[70:71]
	v_pk_add_f32 v[60:61], v[60:61], v[62:63]
	v_pk_fma_f32 v[68:69], v[8:9], v[8:9], v[72:73] op_sel_hi:[1,1,0]
	v_pk_fma_f32 v[72:73], v[10:11], v[10:11], v[74:75] op_sel_hi:[1,1,0]
	s_waitcnt vmcnt(3)
	v_mul_f32_e32 v55, v28, v28
	v_mul_f32_e32 v77, v29, v29
	v_pk_add_f32 v[64:65], v[64:65], v[64:65] op_sel:[0,1] op_sel_hi:[1,0]
	v_pk_add_f32 v[60:61], v[60:61], v[60:61] op_sel:[0,1] op_sel_hi:[1,0]
	v_pk_mul_f32 v[66:67], v[14:15], v[14:15]
	v_pk_mul_f32 v[70:71], v[12:13], v[12:13]
	v_mul_f32_e32 v69, v30, v30
	v_mul_f32_e32 v73, v31, v31
	v_mov_b32_e32 v65, v77
	v_mov_b32_e32 v61, v55
	v_pk_mov_b32 v[62:63], v[70:71], v[66:67] op_sel:[1,0]
	v_mov_b32_e32 v71, v67
	v_pk_add_f32 v[68:69], v[68:69], v[72:73]
	v_pk_add_f32 v[60:61], v[60:61], v[64:65]
	s_waitcnt vmcnt(1)
	v_mul_f32_e32 v74, v17, v17
	v_mul_f32_e32 v76, v19, v19
	v_pk_add_f32 v[62:63], v[62:63], v[70:71]
	v_pk_add_f32 v[60:61], v[60:61], v[68:69]
	v_mul_f32_e32 v78, v2, v2
	v_mul_f32_e32 v79, v3, v3
	v_mul_f32_e32 v80, v0, v0
	v_mul_f32_e32 v81, v1, v1
	v_pk_fma_f32 v[66:67], v[16:17], v[16:17], v[74:75] op_sel_hi:[1,1,0]
	v_pk_fma_f32 v[74:75], v[18:19], v[18:19], v[76:77] op_sel_hi:[1,1,0]
	v_pk_add_f32 v[62:63], v[62:63], v[62:63] op_sel:[0,1] op_sel_hi:[1,0]
	v_pk_add_f32 v[60:61], v[60:61], v[60:61] op_sel:[0,1] op_sel_hi:[1,0]
	v_mov_b32_e32 v67, v78
	v_mov_b32_e32 v75, v79
	v_mov_b32_e32 v63, v81
	v_mov_b32_e32 v61, v80
	v_pk_add_f32 v[66:67], v[66:67], v[74:75]
	v_pk_add_f32 v[60:61], v[60:61], v[62:63]
	s_nop 0
	v_pk_add_f32 v[60:61], v[60:61], v[66:67]
	s_nop 0
	v_add_f32_e32 v55, v60, v61
	ds_bpermute_b32 v60, v47, v55
	s_waitcnt lgkmcnt(0)
	v_add_f32_e32 v55, v55, v60
	ds_bpermute_b32 v60, v48, v55
	s_waitcnt lgkmcnt(0)
	v_add_f32_e32 v55, v55, v60
	ds_bpermute_b32 v60, v49, v55
	s_waitcnt lgkmcnt(0)
	v_add_f32_e32 v55, v55, v60
	ds_bpermute_b32 v60, v50, v55
	s_waitcnt lgkmcnt(0)
	v_add_f32_e32 v55, v55, v60
	ds_bpermute_b32 v60, v51, v55
	s_waitcnt lgkmcnt(0)
	v_add_f32_e32 v55, v55, v60
	ds_bpermute_b32 v60, v52, v55
	s_waitcnt lgkmcnt(0)
	v_add_f32_e32 v55, v55, v60
	v_fmamk_f32 v55, v55, 0x3a000000, v53
	v_mul_f32_e32 v60, 0x4f800000, v55
	v_cmp_gt_f32_e32 vcc, s16, v55
	s_nop 1
	v_cndmask_b32_e32 v55, v55, v60, vcc
	v_sqrt_f32_e32 v60, v55
	s_nop 0
	v_add_u32_e32 v61, -1, v60
	v_add_u32_e32 v62, 1, v60
	v_fma_f32 v63, -v61, v60, v55
	v_fma_f32 v64, -v62, v60, v55
	v_cmp_ge_f32_e64 s[4:5], 0, v63
	s_nop 1
	v_cndmask_b32_e64 v60, v60, v61, s[4:5]
	v_cmp_lt_f32_e64 s[4:5], 0, v64
	s_nop 1
	v_cndmask_b32_e64 v60, v60, v62, s[4:5]
	v_mul_f32_e32 v61, 0x37800000, v60
	v_cndmask_b32_e32 v60, v60, v61, vcc
	v_cmp_class_f32_e32 vcc, v55, v54
	s_nop 1
	v_cndmask_b32_e32 v55, v60, v55, vcc
	v_div_scale_f32 v62, s[4:5], v55, v55, 1.0
	v_rcp_f32_e32 v63, v62
	v_div_scale_f32 v64, vcc, 1.0, v55, 1.0
	v_lshl_add_u64 v[60:61], v[36:37], 0, s[12:13]
	v_fma_f32 v65, -v62, v63, 1.0
	v_fmac_f32_e32 v63, v65, v63
	v_mul_f32_e32 v65, v64, v63
	v_fma_f32 v66, -v62, v65, v64
	v_fmac_f32_e32 v65, v66, v63
	v_fma_f32 v62, -v62, v65, v64
	v_div_fmas_f32 v62, v62, v63, v65
	v_div_fixup_f32 v62, v62, v55, 1.0
	v_pk_mul_f32 v[24:25], v[24:25], v[62:63] op_sel_hi:[1,0]
	v_pk_mul_f32 v[26:27], v[26:27], v[62:63] op_sel_hi:[1,0]
	s_waitcnt vmcnt(0)
	v_pk_mul_f32 v[24:25], v[56:57], v[24:25]
	v_pk_mul_f32 v[26:27], v[58:59], v[26:27]
	v_cvt_pk_bf16_f32 v24, v24, v25
	v_cvt_pk_bf16_f32 v25, v26, v27
	global_store_dwordx2 v[60:61], v[24:25], off
	global_load_dwordx4 v[24:27], v[34:35], off offset:1024 nt
	v_pk_mul_f32 v[4:5], v[4:5], v[62:63] op_sel_hi:[1,0]
	v_pk_mul_f32 v[6:7], v[6:7], v[62:63] op_sel_hi:[1,0]
	v_pk_mul_f32 v[20:21], v[20:21], v[62:63] op_sel_hi:[1,0]
	v_pk_mul_f32 v[22:23], v[22:23], v[62:63] op_sel_hi:[1,0]
	v_pk_mul_f32 v[8:9], v[8:9], v[62:63] op_sel_hi:[1,0]
	v_pk_mul_f32 v[10:11], v[10:11], v[62:63] op_sel_hi:[1,0]
	v_pk_mul_f32 v[0:1], v[0:1], v[62:63] op_sel_hi:[1,0]
	v_pk_mul_f32 v[2:3], v[2:3], v[62:63] op_sel_hi:[1,0]
	s_waitcnt vmcnt(0)
	v_pk_mul_f32 v[4:5], v[24:25], v[4:5]
	v_pk_mul_f32 v[6:7], v[26:27], v[6:7]
	v_cvt_pk_bf16_f32 v4, v4, v5
	v_cvt_pk_bf16_f32 v5, v6, v7
	global_store_dwordx2 v[60:61], v[4:5], off offset:512
	global_load_dwordx4 v[4:7], v[34:35], off offset:2048 nt
	s_waitcnt vmcnt(0)
	v_pk_mul_f32 v[4:5], v[4:5], v[20:21]
	v_pk_mul_f32 v[6:7], v[6:7], v[22:23]
	v_cvt_pk_bf16_f32 v4, v4, v5
	v_cvt_pk_bf16_f32 v5, v6, v7
	global_store_dwordx2 v[60:61], v[4:5], off offset:1024
	global_load_dwordx4 v[4:7], v[34:35], off offset:3072 nt
	s_waitcnt vmcnt(0)
	v_pk_mul_f32 v[4:5], v[8:9], v[4:5]
	v_pk_mul_f32 v[6:7], v[10:11], v[6:7]
	v_cvt_pk_bf16_f32 v4, v4, v5
	v_cvt_pk_bf16_f32 v5, v6, v7
	global_store_dwordx2 v[60:61], v[4:5], off offset:1536
	global_load_dwordx4 v[4:7], v[38:39], off nt
	v_pk_mul_f32 v[8:9], v[28:29], v[62:63] op_sel_hi:[1,0]
	v_pk_mul_f32 v[10:11], v[30:31], v[62:63] op_sel_hi:[1,0]
	s_waitcnt vmcnt(0)
	v_pk_mul_f32 v[4:5], v[8:9], v[4:5]
	v_pk_mul_f32 v[6:7], v[10:11], v[6:7]
	v_cvt_pk_bf16_f32 v4, v4, v5
	v_cvt_pk_bf16_f32 v5, v6, v7
	global_store_dwordx2 v[60:61], v[4:5], off offset:2048
	global_load_dwordx4 v[4:7], v[40:41], off nt
	v_pk_mul_f32 v[8:9], v[12:13], v[62:63] op_sel_hi:[1,0]
	v_pk_mul_f32 v[10:11], v[14:15], v[62:63] op_sel_hi:[1,0]
	s_waitcnt vmcnt(0)
	v_pk_mul_f32 v[4:5], v[8:9], v[4:5]
	v_pk_mul_f32 v[6:7], v[10:11], v[6:7]
	v_cvt_pk_bf16_f32 v4, v4, v5
	v_cvt_pk_bf16_f32 v5, v6, v7
	global_store_dwordx2 v[60:61], v[4:5], off offset:2560
	global_load_dwordx4 v[4:7], v[42:43], off nt
	v_pk_mul_f32 v[8:9], v[16:17], v[62:63] op_sel_hi:[1,0]
	v_pk_mul_f32 v[10:11], v[18:19], v[62:63] op_sel_hi:[1,0]
	s_waitcnt vmcnt(0)
	v_pk_mul_f32 v[4:5], v[8:9], v[4:5]
	v_pk_mul_f32 v[6:7], v[10:11], v[6:7]
	v_cvt_pk_bf16_f32 v4, v4, v5
	v_cvt_pk_bf16_f32 v5, v6, v7
	global_store_dwordx2 v[60:61], v[4:5], off offset:3072
	global_load_dwordx4 v[4:7], v[44:45], off nt
	s_waitcnt vmcnt(0)
	v_pk_mul_f32 v[0:1], v[0:1], v[4:5]
	v_pk_mul_f32 v[2:3], v[2:3], v[6:7]
	v_cvt_pk_bf16_f32 v0, v0, v1
	v_cvt_pk_bf16_f32 v1, v2, v3
	global_store_dwordx2 v[60:61], v[0:1], off offset:3584
	s_cbranch_scc1 .LBB0_33
